# P8 GEMM K-loop: 12 of 16 LDS-DMA loads per iteration in scalar-base + 32-bit VGPR offset form
# baseline (speedup 1.0000x reference)
; #define PG8_STAGE(bufoff, gbase, voff) do { _Pragma("unroll") for (int _i = 0; _i < 2; ++_i) \
;         __builtin_amdgcn_global_load_lds((const unsigned*)((const char*)(gbase) + (voff)[_i]), (PG8_LAS unsigned*)(lds + (bufoff) + ldsw + _i * 8192), 16, 0, 0); } while (0)
; #define PG8_LDA(dst, b, h) do { _Pragma("unroll") for (int m = 0; m < 4; ++m) _Pragma("unroll") for (int k = 0; k < 2; ++k) dst[m][k] = *(const PG8_LAS bf16x8*)(lds + PG8_SA(b, h) + aoff + m * 2048 + k * 1024); } while (0)
; #define PG8_LDB(dst, b, h) do { _Pragma("unroll") for (int n = 0; n < 2; ++n) _Pragma("unroll") for (int k = 0; k < 2; ++k) dst[n][k] = *(const PG8_LAS bf16x8*)(lds + PG8_SB(b, h) + boff + n * 2048 + k * 1024); } while (0)
; #define PG8_MMA(ai, bj, At, Bt) do { __builtin_amdgcn_s_setprio(1); _Pragma("unroll") for (int m = 0; m < 4; ++m) _Pragma("unroll") for (int n = 0; n < 2; ++n) _Pragma("unroll") for (int k = 0; k < 2; ++k) \
;         acc[ai][bj][m][n] = __builtin_amdgcn_mfma_f32_16x16x32_bf16(Bt[n][k], At[m][k], acc[ai][bj][m][n], 0, 0, 0); __builtin_amdgcn_s_setprio(0); } while (0)
; #define PG8_WAIT_V(n) asm volatile("s_waitcnt vmcnt(" #n ")" ::: "memory")
; #define PG8_WAIT_L(n) asm volatile("s_waitcnt lgkmcnt(" #n ")" ::: "memory")
; #define PG8_BAR __builtin_amdgcn_s_barrier()
; #define PG8_SCHED __builtin_amdgcn_sched_barrier(0)
; template <class Epi>
; __device__ __forceinline__ void gemm_phase(PG8_LAS unsigned char* lds, const Gemm g, const StaticOrder& S, const Epi& E) {
;     ...
;             PG8_LDB(B0, 0, 0); PG8_SCHED; PG8_LDA(At, 0, 0); PG8_STAGE(PG8_SA(1, 1), a1 + hstep, voffA);
;             PG8_WAIT_L(8); PG8_BAR; PG8_WAIT_L(0); PG8_MMA(0, 0, At, B0); PG8_BAR; PG8_SCHED;
;             PG8_LDB(B1, 0, 1); PG8_STAGE(PG8_SB(0, 0), b2, voffB);
;             PG8_BAR; PG8_WAIT_L(0); PG8_MMA(0, 1, At, B1); PG8_BAR;
;             PG8_LDA(At, 0, 1); PG8_STAGE(PG8_SA(0, 0), a2, voffA);
;             PG8_BAR; PG8_WAIT_L(0); PG8_MMA(1, 0, At, B0); PG8_BAR; PG8_SCHED;
;             PG8_STAGE(PG8_SB(0, 1), b2 + hstep, voffB);
;             PG8_WAIT_V(6); PG8_BAR; PG8_MMA(1, 1, At, B1); PG8_BAR;
;             PG8_LDB(B0, 1, 0); PG8_SCHED; PG8_LDA(At, 1, 0); PG8_STAGE(PG8_SA(0, 1), a2 + hstep, voffA);
;             PG8_WAIT_L(8); PG8_BAR; PG8_WAIT_L(0); PG8_MMA(0, 0, At, B0); PG8_BAR; PG8_SCHED;
.LBB0_722:
	ds_read_b128 v[150:153], v159
	ds_read_b128 v[154:157], v159 offset:1024
	ds_read_b128 v[162:165], v159 offset:2048
	ds_read_b128 v[166:169], v159 offset:3072
	s_add_u32 s22, s20, 0xfff80080
	s_addc_u32 s23, s21, -1
	s_cmp_eq_u32 s50, 28
	s_cselect_b32 s25, s3, s23
	s_cselect_b32 s24, s5, s22
	s_cselect_b32 s23, s13, s49
	s_cselect_b32 s22, s15, s48
	v_lshl_add_u64 v[202:203], s[20:21], 0, v[142:143]
	s_add_i32 m0, s30, 0xc000
	ds_read_b128 v[170:173], v160
	ds_read_b128 v[174:177], v160 offset:1024
	ds_read_b128 v[178:181], v160 offset:2048
	ds_read_b128 v[182:185], v160 offset:3072
	ds_read_b128 v[186:189], v160 offset:4096
	ds_read_b128 v[190:193], v160 offset:5120
	ds_read_b128 v[194:197], v160 offset:6144
	ds_read_b128 v[198:201], v160 offset:7168
	global_load_lds_dwordx4 v142, s[20:21]
	v_lshl_add_u64 v[202:203], s[20:21], 0, v[144:145]
	s_add_i32 m0, s30, 0xe000
	s_nop 0
	global_load_lds_dwordx4 v144, s[20:21]
	s_waitcnt lgkmcnt(8)
	s_barrier
	s_waitcnt lgkmcnt(0)
	s_setprio 1
	s_waitcnt lgkmcnt(0)
	v_mfma_f32_16x16x32_bf16 v[126:129], v[150:153], v[170:173], v[126:129]
	v_mfma_f32_16x16x32_bf16 v[122:125], v[162:165], v[170:173], v[122:125]
	v_mfma_f32_16x16x32_bf16 v[110:113], v[150:153], v[178:181], v[110:113]
	v_mfma_f32_16x16x32_bf16 v[106:109], v[162:165], v[178:181], v[106:109]
	v_mfma_f32_16x16x32_bf16 v[94:97], v[150:153], v[186:189], v[94:97]
	v_mfma_f32_16x16x32_bf16 v[90:93], v[162:165], v[186:189], v[90:93]
	v_mfma_f32_16x16x32_bf16 v[78:81], v[150:153], v[194:197], v[78:81]
	v_mfma_f32_16x16x32_bf16 v[74:77], v[162:165], v[194:197], v[74:77]
	v_mfma_f32_16x16x32_bf16 v[126:129], v[154:157], v[174:177], v[126:129]
	v_mfma_f32_16x16x32_bf16 v[122:125], v[166:169], v[174:177], v[122:125]
	v_mfma_f32_16x16x32_bf16 v[110:113], v[154:157], v[182:185], v[110:113]
	v_mfma_f32_16x16x32_bf16 v[106:109], v[166:169], v[182:185], v[106:109]
	v_mfma_f32_16x16x32_bf16 v[94:97], v[154:157], v[190:193], v[94:97]
	v_mfma_f32_16x16x32_bf16 v[90:93], v[166:169], v[190:193], v[90:93]
	v_mfma_f32_16x16x32_bf16 v[78:81], v[154:157], v[198:201], v[78:81]
	v_mfma_f32_16x16x32_bf16 v[74:77], v[166:169], v[198:201], v[74:77]
	s_setprio 0
	s_barrier
	s_add_i32 s51, s43, s29
	v_lshl_add_u64 v[218:219], s[22:23], 0, v[134:135]
	s_mov_b32 m0, s51
	ds_read_b128 v[202:205], v161
	ds_read_b128 v[206:209], v161 offset:1024
	ds_read_b128 v[210:213], v161 offset:2048
	ds_read_b128 v[214:217], v161 offset:3072
	global_load_lds_dwordx4 v134, s[22:23]
	v_lshl_add_u64 v[220:221], s[22:23], 0, v[138:139]
	s_add_i32 m0, s51, 0x2000
	s_nop 0
	global_load_lds_dwordx4 v138, s[22:23]
	s_barrier
	s_waitcnt lgkmcnt(0)
	s_setprio 1
	s_waitcnt lgkmcnt(0)
	v_mfma_f32_16x16x32_bf16 v[118:121], v[202:205], v[170:173], v[118:121]
	v_mfma_f32_16x16x32_bf16 v[114:117], v[210:213], v[170:173], v[114:117]
	v_mfma_f32_16x16x32_bf16 v[102:105], v[202:205], v[178:181], v[102:105]
	v_mfma_f32_16x16x32_bf16 v[98:101], v[210:213], v[178:181], v[98:101]
	v_mfma_f32_16x16x32_bf16 v[86:89], v[202:205], v[186:189], v[86:89]
	v_mfma_f32_16x16x32_bf16 v[82:85], v[210:213], v[186:189], v[82:85]
	v_mfma_f32_16x16x32_bf16 v[70:73], v[202:205], v[194:197], v[70:73]
	v_mfma_f32_16x16x32_bf16 v[66:69], v[210:213], v[194:197], v[66:69]
	v_mfma_f32_16x16x32_bf16 v[118:121], v[206:209], v[174:177], v[118:121]
	v_mfma_f32_16x16x32_bf16 v[114:117], v[214:217], v[174:177], v[114:117]
	v_mfma_f32_16x16x32_bf16 v[102:105], v[206:209], v[182:185], v[102:105]
	v_mfma_f32_16x16x32_bf16 v[98:101], v[214:217], v[182:185], v[98:101]
	v_mfma_f32_16x16x32_bf16 v[86:89], v[206:209], v[190:193], v[86:89]
	v_mfma_f32_16x16x32_bf16 v[82:85], v[214:217], v[190:193], v[82:85]
	v_mfma_f32_16x16x32_bf16 v[70:73], v[206:209], v[198:201], v[70:73]
	v_mfma_f32_16x16x32_bf16 v[66:69], v[214:217], v[198:201], v[66:69]
	s_setprio 0
	s_mov_b32 m0, s30
	v_lshl_add_u64 v[222:223], s[24:25], 0, v[132:133]
	s_barrier
	ds_read_b128 v[170:173], v160 offset:16384
	ds_read_b128 v[174:177], v160 offset:17408
	ds_read_b128 v[178:181], v160 offset:18432
	ds_read_b128 v[182:185], v160 offset:19456
	ds_read_b128 v[186:189], v160 offset:20480
	ds_read_b128 v[190:193], v160 offset:21504
	ds_read_b128 v[194:197], v160 offset:22528
	ds_read_b128 v[198:201], v160 offset:23552
	global_load_lds_dwordx4 v132, s[24:25]
	v_lshl_add_u64 v[224:225], s[24:25], 0, v[136:137]
	s_mov_b32 m0, s31
	s_nop 0
	global_load_lds_dwordx4 v136, s[24:25]
	s_barrier
	s_waitcnt lgkmcnt(0)
	s_setprio 1
	s_waitcnt lgkmcnt(0)
	v_mfma_f32_16x16x32_bf16 v[62:65], v[150:153], v[170:173], v[62:65]
	v_mfma_f32_16x16x32_bf16 v[58:61], v[162:165], v[170:173], v[58:61]
	v_mfma_f32_16x16x32_bf16 v[46:49], v[150:153], v[178:181], v[46:49]
	v_mfma_f32_16x16x32_bf16 v[42:45], v[162:165], v[178:181], v[42:45]
	v_mfma_f32_16x16x32_bf16 v[30:33], v[150:153], v[186:189], v[30:33]
	v_mfma_f32_16x16x32_bf16 v[26:29], v[162:165], v[186:189], v[26:29]
	v_mfma_f32_16x16x32_bf16 v[14:17], v[150:153], v[194:197], v[14:17]
	v_mfma_f32_16x16x32_bf16 v[10:13], v[162:165], v[194:197], v[10:13]
	v_mfma_f32_16x16x32_bf16 v[62:65], v[154:157], v[174:177], v[62:65]
	v_mfma_f32_16x16x32_bf16 v[58:61], v[166:169], v[174:177], v[58:61]
	v_mfma_f32_16x16x32_bf16 v[46:49], v[154:157], v[182:185], v[46:49]
	v_mfma_f32_16x16x32_bf16 v[42:45], v[166:169], v[182:185], v[42:45]
	v_mfma_f32_16x16x32_bf16 v[30:33], v[154:157], v[190:193], v[30:33]
	v_mfma_f32_16x16x32_bf16 v[26:29], v[166:169], v[190:193], v[26:29]
	v_mfma_f32_16x16x32_bf16 v[14:17], v[154:157], v[198:201], v[14:17]
	v_mfma_f32_16x16x32_bf16 v[10:13], v[166:169], v[198:201], v[10:13]
	s_setprio 0
	s_barrier
; #define PG8_STAGE(bufoff, gbase, voff) do { _Pragma("unroll") for (int _i = 0; _i < 2; ++_i) \
;         __builtin_amdgcn_global_load_lds((const unsigned*)((const char*)(gbase) + (voff)[_i]), (PG8_LAS unsigned*)(lds + (bufoff) + ldsw + _i * 8192), 16, 0, 0); } while (0)
; #define PG8_LDA(dst, b, h) do { _Pragma("unroll") for (int m = 0; m < 4; ++m) _Pragma("unroll") for (int k = 0; k < 2; ++k) dst[m][k] = *(const PG8_LAS bf16x8*)(lds + PG8_SA(b, h) + aoff + m * 2048 + k * 1024); } while (0)
; #define PG8_LDB(dst, b, h) do { _Pragma("unroll") for (int n = 0; n < 2; ++n) _Pragma("unroll") for (int k = 0; k < 2; ++k) dst[n][k] = *(const PG8_LAS bf16x8*)(lds + PG8_SB(b, h) + boff + n * 2048 + k * 1024); } while (0)
; #define PG8_MMA(ai, bj, At, Bt) do { __builtin_amdgcn_s_setprio(1); _Pragma("unroll") for (int m = 0; m < 4; ++m) _Pragma("unroll") for (int n = 0; n < 2; ++n) _Pragma("unroll") for (int k = 0; k < 2; ++k) \
;         acc[ai][bj][m][n] = __builtin_amdgcn_mfma_f32_16x16x32_bf16(Bt[n][k], At[m][k], acc[ai][bj][m][n], 0, 0, 0); __builtin_amdgcn_s_setprio(0); } while (0)
; #define PG8_WAIT_V(n) asm volatile("s_waitcnt vmcnt(" #n ")" ::: "memory")
; #define PG8_WAIT_L(n) asm volatile("s_waitcnt lgkmcnt(" #n ")" ::: "memory")
; #define PG8_BAR __builtin_amdgcn_s_barrier()
; #define PG8_SCHED __builtin_amdgcn_sched_barrier(0)
; template <class Epi>
; __device__ __forceinline__ void gemm_phase(PG8_LAS unsigned char* lds, const Gemm g, const StaticOrder& S, const Epi& E) {
;     ...
;             PG8_WAIT_V(6); PG8_BAR; PG8_MMA(1, 1, At, B1); PG8_BAR;
;             PG8_LDB(B0, 1, 0); PG8_SCHED; PG8_LDA(At, 1, 0); PG8_STAGE(PG8_SA(0, 1), a2 + hstep, voffA);
;             PG8_WAIT_L(8); PG8_BAR; PG8_WAIT_L(0); PG8_MMA(0, 0, At, B0); PG8_BAR; PG8_SCHED;
;             PG8_LDB(B1, 1, 1); PG8_STAGE(PG8_SB(1, 0), b3, voffB);
;             PG8_BAR; PG8_WAIT_L(0); PG8_MMA(0, 1, At, B1); PG8_BAR;
;             PG8_LDA(At, 1, 1); PG8_STAGE(PG8_SA(1, 0), a3, voffA);
;             PG8_BAR; PG8_WAIT_L(0); PG8_MMA(1, 0, At, B0); PG8_BAR; PG8_SCHED;
	s_add_u32 s52, s22, 0x80000
	s_addc_u32 s53, s23, 0
	s_add_i32 s51, s44, s29
	v_lshl_add_u64 v[150:151], s[52:53], 0, v[134:135]
	s_mov_b32 m0, s51
	s_nop 0
	global_load_lds_dwordx4 v134, s[52:53]
	v_lshl_add_u64 v[150:151], s[52:53], 0, v[138:139]
	s_add_i32 m0, s51, 0x2000
	s_nop 0
	global_load_lds_dwordx4 v138, s[52:53]
	s_waitcnt vmcnt(6)
	s_barrier
	s_setprio 1
	v_mfma_f32_16x16x32_bf16 v[54:57], v[202:205], v[170:173], v[54:57]
	v_mfma_f32_16x16x32_bf16 v[50:53], v[210:213], v[170:173], v[50:53]
	v_mfma_f32_16x16x32_bf16 v[38:41], v[202:205], v[178:181], v[38:41]
	v_mfma_f32_16x16x32_bf16 v[34:37], v[210:213], v[178:181], v[34:37]
	v_mfma_f32_16x16x32_bf16 v[22:25], v[202:205], v[186:189], v[22:25]
	v_mfma_f32_16x16x32_bf16 v[18:21], v[210:213], v[186:189], v[18:21]
	v_mfma_f32_16x16x32_bf16 v[6:9], v[202:205], v[194:197], v[6:9]
	v_mfma_f32_16x16x32_bf16 v[2:5], v[210:213], v[194:197], v[2:5]
	v_mfma_f32_16x16x32_bf16 v[54:57], v[206:209], v[174:177], v[54:57]
	v_mfma_f32_16x16x32_bf16 v[50:53], v[214:217], v[174:177], v[50:53]
	v_mfma_f32_16x16x32_bf16 v[38:41], v[206:209], v[182:185], v[38:41]
	v_mfma_f32_16x16x32_bf16 v[34:37], v[214:217], v[182:185], v[34:37]
	v_mfma_f32_16x16x32_bf16 v[22:25], v[206:209], v[190:193], v[22:25]
	v_mfma_f32_16x16x32_bf16 v[18:21], v[214:217], v[190:193], v[18:21]
	v_mfma_f32_16x16x32_bf16 v[6:9], v[206:209], v[198:201], v[6:9]
	v_mfma_f32_16x16x32_bf16 v[2:5], v[214:217], v[198:201], v[2:5]
	s_setprio 0
	s_add_i32 s51, 0, 0x18000
	v_add_u32_e32 v140, s51, v131
	s_barrier
	ds_read_b128 v[150:153], v140
	ds_read_b128 v[154:157], v140 offset:1024
	ds_read_b128 v[162:165], v140 offset:2048
	ds_read_b128 v[166:169], v140 offset:3072
	s_add_u32 s24, s24, 0x80000
	s_addc_u32 s25, s25, 0
	s_mov_b32 m0, s33
	v_lshl_add_u64 v[202:203], s[24:25], 0, v[132:133]
	ds_read_b128 v[170:173], v160 offset:32768
	ds_read_b128 v[174:177], v160 offset:33792
	ds_read_b128 v[178:181], v160 offset:34816
	ds_read_b128 v[182:185], v160 offset:35840
	ds_read_b128 v[186:189], v160 offset:36864
	ds_read_b128 v[190:193], v160 offset:37888
	ds_read_b128 v[194:197], v160 offset:38912
	ds_read_b128 v[198:201], v160 offset:39936
	global_load_lds_dwordx4 v132, s[24:25]
	v_lshl_add_u64 v[202:203], s[24:25], 0, v[136:137]
	s_mov_b32 m0, s34
	s_nop 0
	global_load_lds_dwordx4 v136, s[24:25]
	s_waitcnt lgkmcnt(8)
	s_barrier
	s_waitcnt lgkmcnt(0)
	s_setprio 1
	s_waitcnt lgkmcnt(0)
	v_mfma_f32_16x16x32_bf16 v[126:129], v[150:153], v[170:173], v[126:129]
	v_mfma_f32_16x16x32_bf16 v[122:125], v[162:165], v[170:173], v[122:125]
	v_mfma_f32_16x16x32_bf16 v[110:113], v[150:153], v[178:181], v[110:113]
	v_mfma_f32_16x16x32_bf16 v[106:109], v[162:165], v[178:181], v[106:109]
	v_mfma_f32_16x16x32_bf16 v[94:97], v[150:153], v[186:189], v[94:97]
	v_mfma_f32_16x16x32_bf16 v[90:93], v[162:165], v[186:189], v[90:93]
	v_mfma_f32_16x16x32_bf16 v[78:81], v[150:153], v[194:197], v[78:81]
	v_mfma_f32_16x16x32_bf16 v[74:77], v[162:165], v[194:197], v[74:77]
	v_mfma_f32_16x16x32_bf16 v[126:129], v[154:157], v[174:177], v[126:129]
	v_mfma_f32_16x16x32_bf16 v[122:125], v[166:169], v[174:177], v[122:125]
	v_mfma_f32_16x16x32_bf16 v[110:113], v[154:157], v[182:185], v[110:113]
	v_mfma_f32_16x16x32_bf16 v[106:109], v[166:169], v[182:185], v[106:109]
	v_mfma_f32_16x16x32_bf16 v[94:97], v[154:157], v[190:193], v[94:97]
	v_mfma_f32_16x16x32_bf16 v[90:93], v[166:169], v[190:193], v[90:93]
	v_mfma_f32_16x16x32_bf16 v[78:81], v[154:157], v[198:201], v[78:81]
	v_mfma_f32_16x16x32_bf16 v[74:77], v[166:169], v[198:201], v[74:77]
	s_setprio 0
	s_barrier
	s_add_i32 s24, 0, 0x1c000
	s_add_i32 s25, s51, s29
	v_add_u32_e32 v140, s24, v131
	v_lshl_add_u64 v[218:219], v[218:219], 0, s[10:11]
	s_mov_b32 m0, s25
	ds_read_b128 v[202:205], v140
	ds_read_b128 v[206:209], v140 offset:1024
	ds_read_b128 v[210:213], v140 offset:2048
	ds_read_b128 v[214:217], v140 offset:3072
	global_load_lds_dwordx4 v[218:219], off
	v_lshl_add_u64 v[218:219], v[220:221], 0, s[10:11]
	s_add_i32 m0, s25, 0x2000
	s_nop 0
	global_load_lds_dwordx4 v[218:219], off
	s_barrier
	s_waitcnt lgkmcnt(0)
	s_setprio 1
	s_waitcnt lgkmcnt(0)
	v_mfma_f32_16x16x32_bf16 v[118:121], v[202:205], v[170:173], v[118:121]
	v_mfma_f32_16x16x32_bf16 v[114:117], v[210:213], v[170:173], v[114:117]
	v_mfma_f32_16x16x32_bf16 v[102:105], v[202:205], v[178:181], v[102:105]
	v_mfma_f32_16x16x32_bf16 v[98:101], v[210:213], v[178:181], v[98:101]
	v_mfma_f32_16x16x32_bf16 v[86:89], v[202:205], v[186:189], v[86:89]
	v_mfma_f32_16x16x32_bf16 v[82:85], v[210:213], v[186:189], v[82:85]
	v_mfma_f32_16x16x32_bf16 v[70:73], v[202:205], v[194:197], v[70:73]
	v_mfma_f32_16x16x32_bf16 v[66:69], v[210:213], v[194:197], v[66:69]
	v_mfma_f32_16x16x32_bf16 v[118:121], v[206:209], v[174:177], v[118:121]
	v_mfma_f32_16x16x32_bf16 v[114:117], v[214:217], v[174:177], v[114:117]
	v_mfma_f32_16x16x32_bf16 v[102:105], v[206:209], v[182:185], v[102:105]
	v_mfma_f32_16x16x32_bf16 v[98:101], v[214:217], v[182:185], v[98:101]
	v_mfma_f32_16x16x32_bf16 v[86:89], v[206:209], v[190:193], v[86:89]
	v_mfma_f32_16x16x32_bf16 v[82:85], v[214:217], v[190:193], v[82:85]
	v_mfma_f32_16x16x32_bf16 v[70:73], v[206:209], v[198:201], v[70:73]
	v_mfma_f32_16x16x32_bf16 v[66:69], v[214:217], v[198:201], v[66:69]
	s_setprio 0
	s_mov_b32 m0, s38
	v_lshl_add_u64 v[218:219], v[222:223], 0, s[10:11]
	s_barrier
; #define PG8_STAGE(bufoff, gbase, voff) do { _Pragma("unroll") for (int _i = 0; _i < 2; ++_i) \
;         __builtin_amdgcn_global_load_lds((const unsigned*)((const char*)(gbase) + (voff)[_i]), (PG8_LAS unsigned*)(lds + (bufoff) + ldsw + _i * 8192), 16, 0, 0); } while (0)
; #define PG8_LDA(dst, b, h) do { _Pragma("unroll") for (int m = 0; m < 4; ++m) _Pragma("unroll") for (int k = 0; k < 2; ++k) dst[m][k] = *(const PG8_LAS bf16x8*)(lds + PG8_SA(b, h) + aoff + m * 2048 + k * 1024); } while (0)
; #define PG8_MMA(ai, bj, At, Bt) do { __builtin_amdgcn_s_setprio(1); _Pragma("unroll") for (int m = 0; m < 4; ++m) _Pragma("unroll") for (int n = 0; n < 2; ++n) _Pragma("unroll") for (int k = 0; k < 2; ++k) \
;         acc[ai][bj][m][n] = __builtin_amdgcn_mfma_f32_16x16x32_bf16(Bt[n][k], At[m][k], acc[ai][bj][m][n], 0, 0, 0); __builtin_amdgcn_s_setprio(0); } while (0)
; #define PG8_WAIT_V(n) asm volatile("s_waitcnt vmcnt(" #n ")" ::: "memory")
; #define PG8_WAIT_L(n) asm volatile("s_waitcnt lgkmcnt(" #n ")" ::: "memory")
; #define PG8_BAR __builtin_amdgcn_s_barrier()
; #define PG8_SCHED __builtin_amdgcn_sched_barrier(0)
; template <class Epi>
; __device__ __forceinline__ void gemm_phase(PG8_LAS unsigned char* lds, const Gemm g, const StaticOrder& S, const Epi& E) {
;     ...
;             PG8_LDA(At, 1, 1); PG8_STAGE(PG8_SA(1, 0), a3, voffA);
;             PG8_BAR; PG8_WAIT_L(0); PG8_MMA(1, 0, At, B0); PG8_BAR; PG8_SCHED;
;             PG8_STAGE(PG8_SB(1, 1), b3 + hstep, voffB);
;             PG8_WAIT_V(6); PG8_BAR; PG8_MMA(1, 1, At, B1); PG8_BAR;
	ds_read_b128 v[170:173], v160 offset:49152
	ds_read_b128 v[174:177], v160 offset:50176
	ds_read_b128 v[178:181], v160 offset:51200
	ds_read_b128 v[182:185], v160 offset:52224
	ds_read_b128 v[186:189], v160 offset:53248
	ds_read_b128 v[190:193], v160 offset:54272
	ds_read_b128 v[194:197], v160 offset:55296
	ds_read_b128 v[198:201], v160 offset:56320
	global_load_lds_dwordx4 v[218:219], off
	v_lshl_add_u64 v[218:219], v[224:225], 0, s[10:11]
	s_mov_b32 m0, s39
	s_nop 0
	global_load_lds_dwordx4 v[218:219], off
	s_barrier
	s_waitcnt lgkmcnt(0)
	s_setprio 1
	s_waitcnt lgkmcnt(0)
	v_mfma_f32_16x16x32_bf16 v[62:65], v[150:153], v[170:173], v[62:65]
	v_mfma_f32_16x16x32_bf16 v[58:61], v[162:165], v[170:173], v[58:61]
	v_mfma_f32_16x16x32_bf16 v[46:49], v[150:153], v[178:181], v[46:49]
	v_mfma_f32_16x16x32_bf16 v[42:45], v[162:165], v[178:181], v[42:45]
	v_mfma_f32_16x16x32_bf16 v[30:33], v[150:153], v[186:189], v[30:33]
	v_mfma_f32_16x16x32_bf16 v[26:29], v[162:165], v[186:189], v[26:29]
	v_mfma_f32_16x16x32_bf16 v[14:17], v[150:153], v[194:197], v[14:17]
	v_mfma_f32_16x16x32_bf16 v[10:13], v[162:165], v[194:197], v[10:13]
	v_mfma_f32_16x16x32_bf16 v[62:65], v[154:157], v[174:177], v[62:65]
	v_mfma_f32_16x16x32_bf16 v[58:61], v[166:169], v[174:177], v[58:61]
	v_mfma_f32_16x16x32_bf16 v[46:49], v[154:157], v[182:185], v[46:49]
	v_mfma_f32_16x16x32_bf16 v[42:45], v[166:169], v[182:185], v[42:45]
	v_mfma_f32_16x16x32_bf16 v[30:33], v[154:157], v[190:193], v[30:33]
	v_mfma_f32_16x16x32_bf16 v[26:29], v[166:169], v[190:193], v[26:29]
	v_mfma_f32_16x16x32_bf16 v[14:17], v[154:157], v[198:201], v[14:17]
	v_mfma_f32_16x16x32_bf16 v[10:13], v[166:169], v[198:201], v[10:13]
	s_setprio 0
	s_barrier
	s_add_u32 s22, s22, 0x80080
	s_addc_u32 s23, s23, 0
	s_add_i32 s24, s24, s29
	v_lshl_add_u64 v[150:151], s[22:23], 0, v[134:135]
	s_mov_b32 m0, s24
	s_nop 0
	global_load_lds_dwordx4 v134, s[22:23]
	v_lshl_add_u64 v[150:151], s[22:23], 0, v[138:139]
	s_add_i32 m0, s24, 0x2000
	s_nop 0
	global_load_lds_dwordx4 v138, s[22:23]
	s_waitcnt vmcnt(6)
	s_barrier
	s_setprio 1
	v_mfma_f32_16x16x32_bf16 v[54:57], v[202:205], v[170:173], v[54:57]
	v_mfma_f32_16x16x32_bf16 v[50:53], v[210:213], v[170:173], v[50:53]
	v_mfma_f32_16x16x32_bf16 v[38:41], v[202:205], v[178:181], v[38:41]
	v_mfma_f32_16x16x32_bf16 v[34:37], v[210:213], v[178:181], v[34:37]
	v_mfma_f32_16x16x32_bf16 v[22:25], v[202:205], v[186:189], v[22:25]
	v_mfma_f32_16x16x32_bf16 v[18:21], v[210:213], v[186:189], v[18:21]
	v_mfma_f32_16x16x32_bf16 v[6:9], v[202:205], v[194:197], v[6:9]
	v_mfma_f32_16x16x32_bf16 v[2:5], v[210:213], v[194:197], v[2:5]
	v_mfma_f32_16x16x32_bf16 v[54:57], v[206:209], v[174:177], v[54:57]
	v_mfma_f32_16x16x32_bf16 v[50:53], v[214:217], v[174:177], v[50:53]
	v_mfma_f32_16x16x32_bf16 v[38:41], v[206:209], v[182:185], v[38:41]
	v_mfma_f32_16x16x32_bf16 v[34:37], v[214:217], v[182:185], v[34:37]
	v_mfma_f32_16x16x32_bf16 v[22:25], v[206:209], v[190:193], v[22:25]
	v_mfma_f32_16x16x32_bf16 v[18:21], v[214:217], v[190:193], v[18:21]
	v_mfma_f32_16x16x32_bf16 v[6:9], v[206:209], v[198:201], v[6:9]
	v_mfma_f32_16x16x32_bf16 v[2:5], v[214:217], v[198:201], v[2:5]
	s_setprio 0
	s_add_i32 s50, s50, 2
	s_add_u32 s20, s20, 0x100
	s_addc_u32 s21, s21, 0
	s_add_u32 s48, s48, 0x100
	s_addc_u32 s49, s49, 0
	s_cmp_gt_u32 s50, 29
	s_barrier
	s_cbranch_scc0 .LBB0_722
	v_lshl_add_u32 v152, s2, 8, v1
	s_lshl_b32 s13, s4, 8
	v_or_b32_e32 v150, s13, v158
	v_mad_i64_i32 v[154:155], s[2:3], v152, s45, 0
	v_cmp_lt_i32_e64 s[2:3], s46, v150
	s_and_saveexec_b64 s[20:21], s[2:3]
	s_xor_b64 s[20:21], exec, s[20:21]
	s_cbranch_execz .LBB0_726
	s_cmpk_gt_u32 s13, 0x317f
	s_cbranch_scc1 .LBB0_726
	v_lshl_add_u64 v[156:157], s[8:9], 0, v[154:155]
	v_mov_b32_e32 v151, v141
	v_lshl_add_u64 v[156:157], v[150:151], 1, v[156:157]
	v_add_co_u32_e32 v156, vcc, 0xffffa000, v156
	v_cvt_pk_bf16_f32 v162, v126, v127
	v_cvt_pk_bf16_f32 v163, v128, v129
	v_cvt_pk_bf16_f32 v164, v122, v123
	v_cvt_pk_bf16_f32 v165, v124, v125
	s_nop 1
	v_addc_co_u32_e32 v157, vcc, -1, v157, vcc
	global_store_dwordx4 v[156:157], v[162:165], off
